# attention finalize: the twelve gate / sub-norm gain loads issued together at the top of the finalize instead of four serialized load-wait-store rounds
# speedup vs baseline: 1.0096x; 1.0052x over previous
.LBB0_392:
	s_setprio 0
	v_and_b32_e32 v134, 16, v153
	v_lshrrev_b32_e32 v135, 2, v153
	v_and_or_b32 v134, v135, 8, v134
	v_mov_b64_e32 v[132:133], s[50:51]
	v_mad_u64_u32 v[132:133], s[38:39], v136, s21, v[132:133]
	v_mad_i32_i24 v133, v137, s21, v133
	v_lshl_add_u64 v[132:133], v[132:133], 0, s[30:31]
	v_lshlrev_b32_e32 v134, 1, v134
	v_mov_b32_e32 v135, 0
	v_lshl_add_u64 v[132:133], v[132:133], 0, v[134:135]
	v_lshlrev_b32_e32 v134, 4, v152
	global_load_dwordx4 v[84:87], v[132:133], off offset:1024
	global_load_dwordx4 v[100:103], v134, s[42:43]
	global_load_dwordx4 v[116:119], v134, s[42:43] offset:64
	global_load_dwordx4 v[88:91], v[132:133], off offset:1088
	global_load_dwordx4 v[104:107], v134, s[42:43] offset:128
	global_load_dwordx4 v[120:123], v134, s[42:43] offset:192
	global_load_dwordx4 v[92:95], v[132:133], off offset:1152
	global_load_dwordx4 v[108:111], v134, s[42:43] offset:256
	global_load_dwordx4 v[124:127], v134, s[42:43] offset:320
	global_load_dwordx4 v[96:99], v[132:133], off offset:1216
	global_load_dwordx4 v[112:115], v134, s[42:43] offset:384
	global_load_dwordx4 v[128:131], v134, s[42:43] offset:448
	ds_bpermute_b32 v0, v148, v162
	s_add_i32 s13, s13, s54
	s_add_i32 s8, s8, s54
	s_waitcnt lgkmcnt(0)
	v_add_f32_e32 v0, v162, v0
	ds_bpermute_b32 v2, v149, v0
	s_waitcnt lgkmcnt(0)
	v_add_f32_e32 v0, v0, v2
	ds_bpermute_b32 v2, v148, v160
	s_waitcnt lgkmcnt(0)
	v_add_f32_e32 v2, v160, v2
	ds_bpermute_b32 v3, v149, v2
	s_waitcnt lgkmcnt(0)
	v_add_f32_e32 v2, v2, v3
	v_div_scale_f32 v3, s[38:39], v0, v0, 1.0
	v_rcp_f32_e32 v36, v3
	s_nop 0
	v_fma_f32 v37, -v3, v36, 1.0
	v_fmac_f32_e32 v36, v37, v36
	v_div_scale_f32 v37, vcc, 1.0, v0, 1.0
	v_mul_f32_e32 v38, v37, v36
	v_fma_f32 v39, -v3, v38, v37
	v_fmac_f32_e32 v38, v39, v36
	v_fma_f32 v3, -v3, v38, v37
	v_div_fmas_f32 v3, v3, v36, v38
	v_div_fixup_f32 v0, v3, v0, 1.0
	v_div_scale_f32 v3, s[38:39], v2, v2, v150
	v_rcp_f32_e32 v36, v3
	s_nop 0
	v_fma_f32 v37, -v3, v36, 1.0
	v_fmac_f32_e32 v36, v37, v36
	v_div_scale_f32 v37, vcc, v150, v2, v150
	v_mul_f32_e32 v38, v37, v36
	v_fma_f32 v39, -v3, v38, v37
	v_fmac_f32_e32 v38, v39, v36
	v_fma_f32 v3, -v3, v38, v37
	v_div_fmas_f32 v3, v3, v36, v38
	v_div_fixup_f32 v2, v3, v2, v150
	v_pk_mul_f32 v[36:37], v[80:81], v[2:3] op_sel_hi:[1,0]
	v_pk_mul_f32 v[38:39], v[82:83], v[2:3] op_sel_hi:[1,0]
	v_pk_fma_f32 v[42:43], v[72:73], v[0:1], v[36:37] op_sel_hi:[1,0,1] neg_lo:[0,0,1] neg_hi:[0,0,1]
	v_pk_mul_f32 v[36:37], v[76:77], v[2:3] op_sel_hi:[1,0]
	v_pk_fma_f32 v[40:41], v[74:75], v[0:1], v[38:39] op_sel_hi:[1,0,1] neg_lo:[0,0,1] neg_hi:[0,0,1]
	v_pk_mul_f32 v[38:39], v[78:79], v[2:3] op_sel_hi:[1,0]
	v_pk_fma_f32 v[46:47], v[68:69], v[0:1], v[36:37] op_sel_hi:[1,0,1] neg_lo:[0,0,1] neg_hi:[0,0,1]
	v_pk_fma_f32 v[44:45], v[70:71], v[0:1], v[38:39] op_sel_hi:[1,0,1] neg_lo:[0,0,1] neg_hi:[0,0,1]
	v_mov_b32_e32 v38, v43
	v_mov_b32_e32 v39, v47
	v_mov_b32_e32 v36, v42
	v_mov_b32_e32 v37, v46
	v_pk_mul_f32 v[38:39], v[38:39], v[38:39]
	v_mov_b32_e32 v52, v41
	v_mov_b32_e32 v53, v45
	v_pk_fma_f32 v[36:37], v[36:37], v[36:37], v[38:39]
	v_mov_b32_e32 v38, v40
	v_mov_b32_e32 v39, v44
	v_pk_mul_f32 v[52:53], v[52:53], v[52:53]
	v_pk_mul_f32 v[56:57], v[56:57], v[2:3] op_sel_hi:[1,0]
	v_pk_fma_f32 v[38:39], v[38:39], v[38:39], v[52:53]
	v_pk_mul_f32 v[58:59], v[58:59], v[2:3] op_sel_hi:[1,0]
	v_pk_add_f32 v[36:37], v[36:37], v[38:39]
	v_pk_mul_f32 v[38:39], v[66:67], v[2:3] op_sel_hi:[1,0]
	v_pk_add_f32 v[52:53], v[36:37], v[36:37] op_sel_hi:[0,1]
	v_pk_mul_f32 v[36:37], v[64:65], v[2:3] op_sel_hi:[1,0]
	v_pk_fma_f32 v[38:39], v[62:63], v[0:1], v[38:39] op_sel_hi:[1,0,1] neg_lo:[0,0,1] neg_hi:[0,0,1]
	v_pk_fma_f32 v[36:37], v[60:61], v[0:1], v[36:37] op_sel_hi:[1,0,1] neg_lo:[0,0,1] neg_hi:[0,0,1]
	v_pk_mul_f32 v[54:55], v[38:39], v[38:39]
	v_pk_mul_f32 v[60:61], v[36:37], v[36:37]
	v_pk_fma_f32 v[32:33], v[32:33], v[0:1], v[56:57] op_sel_hi:[1,0,1] neg_lo:[0,0,1] neg_hi:[0,0,1]
	v_pk_mov_b32 v[62:63], v[60:61], v[54:55] op_sel:[1,0]
	v_mov_b32_e32 v61, v55
	v_pk_fma_f32 v[34:35], v[34:35], v[0:1], v[58:59] op_sel_hi:[1,0,1] neg_lo:[0,0,1] neg_hi:[0,0,1]
	v_mul_f32_e32 v52, v32, v32
	v_pk_add_f32 v[54:55], v[62:63], v[60:61]
	v_pk_fma_f32 v[56:57], v[32:33], v[32:33], v[52:53] op_sel_hi:[1,1,0]
	v_mul_f32_e32 v52, v34, v34
	v_pk_mul_f32 v[28:29], v[28:29], v[2:3] op_sel_hi:[1,0]
	v_pk_mul_f32 v[30:31], v[30:31], v[2:3] op_sel_hi:[1,0]
	v_pk_add_f32 v[54:55], v[54:55], v[54:55] op_sel_hi:[0,1]
	v_pk_fma_f32 v[58:59], v[34:35], v[34:35], v[52:53] op_sel_hi:[1,1,0]
	v_pk_fma_f32 v[26:27], v[26:27], v[0:1], v[30:31] op_sel_hi:[1,0,1] neg_lo:[0,0,1] neg_hi:[0,0,1]
	v_pk_fma_f32 v[24:25], v[24:25], v[0:1], v[28:29] op_sel_hi:[1,0,1] neg_lo:[0,0,1] neg_hi:[0,0,1]
	v_pk_mul_f32 v[22:23], v[22:23], v[2:3] op_sel_hi:[1,0]
	v_pk_mul_f32 v[20:21], v[20:21], v[2:3] op_sel_hi:[1,0]
	v_pk_mul_f32 v[12:13], v[12:13], v[2:3] op_sel_hi:[1,0]
	v_mul_f32_e32 v56, v24, v24
	v_mul_f32_e32 v58, v25, v25
	v_mul_f32_e32 v54, v26, v26
	v_mul_f32_e32 v52, v27, v27
	v_pk_fma_f32 v[16:17], v[16:17], v[0:1], v[20:21] op_sel_hi:[1,0,1] neg_lo:[0,0,1] neg_hi:[0,0,1]
	v_pk_fma_f32 v[20:21], v[18:19], v[0:1], v[22:23] op_sel_hi:[1,0,1] neg_lo:[0,0,1] neg_hi:[0,0,1]
	v_pk_mul_f32 v[14:15], v[14:15], v[2:3] op_sel_hi:[1,0]
	v_pk_fma_f32 v[8:9], v[8:9], v[0:1], v[12:13] op_sel_hi:[1,0,1] neg_lo:[0,0,1] neg_hi:[0,0,1]
	v_pk_add_f32 v[28:29], v[56:57], v[58:59]
	v_pk_add_f32 v[30:31], v[54:55], v[52:53]
	v_pk_mul_f32 v[18:19], v[20:21], v[20:21]
	v_pk_mul_f32 v[22:23], v[16:17], v[16:17]
	v_pk_fma_f32 v[10:11], v[10:11], v[0:1], v[14:15] op_sel_hi:[1,0,1] neg_lo:[0,0,1] neg_hi:[0,0,1]
	v_mul_f32_e32 v12, v8, v8
	v_pk_add_f32 v[28:29], v[28:29], v[30:31]
	v_pk_mov_b32 v[30:31], v[22:23], v[18:19] op_sel:[1,0]
	v_mov_b32_e32 v23, v19
	v_pk_fma_f32 v[14:15], v[8:9], v[8:9], v[12:13] op_sel_hi:[1,1,0]
	v_mul_f32_e32 v12, v10, v10
	v_pk_add_f32 v[18:19], v[30:31], v[22:23]
	v_pk_fma_f32 v[22:23], v[10:11], v[10:11], v[12:13] op_sel_hi:[1,1,0]
	v_pk_mul_f32 v[12:13], v[48:49], v[2:3] op_sel_hi:[1,0]
	v_pk_mul_f32 v[2:3], v[50:51], v[2:3] op_sel_hi:[1,0]
	v_pk_add_f32 v[28:29], v[28:29], v[28:29] op_sel_hi:[0,1]
	v_pk_add_f32 v[18:19], v[18:19], v[18:19] op_sel_hi:[0,1]
	v_pk_fma_f32 v[6:7], v[6:7], v[0:1], v[2:3] op_sel_hi:[1,0,1] neg_lo:[0,0,1] neg_hi:[0,0,1]
	v_pk_fma_f32 v[12:13], v[4:5], v[0:1], v[12:13] op_sel_hi:[1,0,1] neg_lo:[0,0,1] neg_hi:[0,0,1]
	v_mul_f32_e32 v18, v6, v6
	v_mul_f32_e32 v14, v12, v12
	v_mul_f32_e32 v22, v13, v13
	v_mul_f32_e32 v28, v7, v7
	v_pk_add_f32 v[2:3], v[14:15], v[22:23]
	v_pk_add_f32 v[4:5], v[18:19], v[28:29]
	s_nop 0
	v_pk_add_f32 v[2:3], v[2:3], v[4:5]
	s_nop 0
	v_add_f32_e32 v0, v2, v3
	ds_bpermute_b32 v2, v148, v0
	s_waitcnt lgkmcnt(0)
	v_add_f32_e32 v0, v0, v2
	ds_bpermute_b32 v2, v149, v0
	s_waitcnt lgkmcnt(0)
	v_add_f32_e32 v0, v0, v2
	v_fmamk_f32 v0, v0, 0x3c000000, v227
	v_cmp_gt_f32_e32 vcc, s7, v0
	v_mul_f32_e32 v2, 0x4f800000, v0
	s_nop 0
	v_cndmask_b32_e32 v0, v0, v2, vcc
	v_sqrt_f32_e32 v2, v0
	s_nop 0
	v_add_u32_e32 v3, -1, v2
	v_fma_f32 v4, -v3, v2, v0
	v_cmp_ge_f32_e64 s[38:39], 0, v4
	v_add_u32_e32 v4, 1, v2
	s_nop 0
	v_cndmask_b32_e64 v3, v2, v3, s[38:39]
	v_fma_f32 v2, -v4, v2, v0
	v_cmp_lt_f32_e64 s[38:39], 0, v2
	s_nop 1
	v_cndmask_b32_e64 v2, v3, v4, s[38:39]
	v_mul_f32_e32 v3, 0x37800000, v2
	v_cndmask_b32_e32 v2, v2, v3, vcc
	v_cmp_class_f32_e32 vcc, v0, v228
	s_nop 1
	v_cndmask_b32_e32 v0, v2, v0, vcc
	v_div_scale_f32 v2, s[38:39], v0, v0, v151
	v_rcp_f32_e32 v3, v2
	s_nop 0
	v_fma_f32 v4, -v2, v3, 1.0
	v_fmac_f32_e32 v3, v4, v3
	v_div_scale_f32 v4, vcc, v151, v0, v151
	v_mul_f32_e32 v5, v4, v3
	v_fma_f32 v14, -v2, v5, v4
	v_fmac_f32_e32 v5, v14, v3
	v_fma_f32 v2, -v2, v5, v4
	v_div_fmas_f32 v2, v2, v3, v5
	v_div_fixup_f32 v18, v2, v0, v151
	v_and_b32_e32 v0, 16, v153
	v_lshrrev_b32_e32 v2, 2, v153
	v_and_or_b32 v0, v2, 8, v0
	v_mov_b64_e32 v[2:3], s[50:51]
	v_mad_u64_u32 v[2:3], s[38:39], v136, s21, v[2:3]
	v_mad_i32_i24 v3, v137, s21, v3
	v_lshl_add_u64 v[2:3], v[2:3], 0, s[30:31]
	v_lshlrev_b32_e32 v0, 1, v0
	v_lshl_add_u64 v[22:23], v[2:3], 0, v[0:1]
	v_lshl_add_u64 v[14:15], v[138:139], 0, v[0:1]
	v_lshlrev_b32_e32 v0, 4, v152
	s_waitcnt vmcnt(0)
	v_mov_b32_e32 v2, v84
	v_mov_b32_e32 v3, v85
	v_mov_b32_e32 v4, v86
	v_mov_b32_e32 v5, v87
	s_nop 1
	v_mov_b32_e32 v28, v100
	v_mov_b32_e32 v29, v101
	v_mov_b32_e32 v30, v102
	v_mov_b32_e32 v31, v103
	s_nop 1
	v_mov_b32_e32 v48, v116
	v_mov_b32_e32 v49, v117
	v_mov_b32_e32 v50, v118
	v_mov_b32_e32 v51, v119
	v_pk_mul_f32 v[40:41], v[40:41], v[18:19] op_sel_hi:[1,0]
	v_pk_mul_f32 v[42:43], v[42:43], v[18:19] op_sel_hi:[1,0]
	v_readlane_b32 s38, v241, 60
	s_add_i32 s9, s9, s38
	s_cmpk_gt_i32 s13, 0xff
	v_readlane_b32 s39, v241, 61
	v_pk_mul_f32 v[30:31], v[30:31], v[40:41]
	v_pk_mul_f32 v[40:41], v[46:47], v[18:19] op_sel_hi:[1,0]
	v_pk_mul_f32 v[28:29], v[28:29], v[42:43]
	v_pk_mul_f32 v[40:41], v[48:49], v[40:41]
	v_pk_mul_f32 v[42:43], v[44:45], v[18:19] op_sel_hi:[1,0]
	s_nop 0
	v_permlane16_swap_b32_e32 v28, v40
	v_permlane16_swap_b32_e32 v29, v41
	v_lshlrev_b32_e32 v19, 16, v2
	v_and_b32_e32 v2, 0xffff0000, v2
	v_pk_mul_f32 v[42:43], v[50:51], v[42:43]
	v_mul_f32_e32 v19, v19, v28
	v_mul_f32_e32 v2, v2, v29
	v_permlane16_swap_b32_e32 v30, v42
	v_permlane16_swap_b32_e32 v31, v43
	v_cvt_pk_bf16_f32 v2, v19, v2
	v_lshlrev_b32_e32 v19, 16, v3
	v_and_b32_e32 v3, 0xffff0000, v3
	v_mul_f32_e32 v19, v19, v30
	v_mul_f32_e32 v3, v3, v31
	v_cvt_pk_bf16_f32 v3, v19, v3
	v_lshlrev_b32_e32 v19, 16, v4
	v_and_b32_e32 v4, 0xffff0000, v4
	v_mul_f32_e32 v19, v19, v40
	v_mul_f32_e32 v4, v4, v41
	v_cvt_pk_bf16_f32 v4, v19, v4
	v_lshlrev_b32_e32 v19, 16, v5
	v_and_b32_e32 v5, 0xffff0000, v5
	v_mul_f32_e32 v5, v5, v43
	v_mul_f32_e32 v19, v19, v42
	v_cvt_pk_bf16_f32 v5, v19, v5
	global_store_dwordx4 v[14:15], v[2:5], off sc1
	s_nop 1
	v_mov_b32_e32 v2, v88
	v_mov_b32_e32 v3, v89
	v_mov_b32_e32 v4, v90
	v_mov_b32_e32 v5, v91
	s_nop 0
	s_nop 1
	v_mov_b32_e32 v28, v104
	v_mov_b32_e32 v29, v105
	v_mov_b32_e32 v30, v106
	v_mov_b32_e32 v31, v107
	s_nop 1
	v_mov_b32_e32 v40, v120
	v_mov_b32_e32 v41, v121
	v_mov_b32_e32 v42, v122
	v_mov_b32_e32 v43, v123
	v_pk_mul_f32 v[36:37], v[36:37], v[18:19] op_sel_hi:[1,0]
	v_pk_mul_f32 v[32:33], v[32:33], v[18:19] op_sel_hi:[1,0]
	v_pk_mul_f32 v[38:39], v[38:39], v[18:19] op_sel_hi:[1,0]
	v_pk_mul_f32 v[34:35], v[34:35], v[18:19] op_sel_hi:[1,0]
	v_lshlrev_b32_e32 v19, 16, v2
	v_pk_mul_f32 v[28:29], v[28:29], v[36:37]
	v_pk_mul_f32 v[32:33], v[40:41], v[32:33]
	v_and_b32_e32 v2, 0xffff0000, v2
	s_nop 0
	v_permlane16_swap_b32_e32 v28, v32
	v_permlane16_swap_b32_e32 v29, v33
	v_pk_mul_f32 v[30:31], v[30:31], v[38:39]
	v_pk_mul_f32 v[34:35], v[42:43], v[34:35]
	v_mul_f32_e32 v19, v19, v28
	v_mul_f32_e32 v2, v2, v29
	v_permlane16_swap_b32_e32 v30, v34
	v_permlane16_swap_b32_e32 v31, v35
	v_cvt_pk_bf16_f32 v2, v19, v2
	v_lshlrev_b32_e32 v19, 16, v3
	v_and_b32_e32 v3, 0xffff0000, v3
	v_mul_f32_e32 v19, v19, v30
	v_mul_f32_e32 v3, v3, v31
	v_cvt_pk_bf16_f32 v3, v19, v3
	v_lshlrev_b32_e32 v19, 16, v4
	v_and_b32_e32 v4, 0xffff0000, v4
	v_mul_f32_e32 v19, v19, v32
	v_mul_f32_e32 v4, v4, v33
	v_cvt_pk_bf16_f32 v4, v19, v4
	v_lshlrev_b32_e32 v19, 16, v5
	v_and_b32_e32 v5, 0xffff0000, v5
	v_mul_f32_e32 v5, v5, v35
	v_mul_f32_e32 v19, v19, v34
	v_cvt_pk_bf16_f32 v5, v19, v5
	global_store_dwordx4 v[14:15], v[2:5], off offset:64 sc1
	s_nop 1
	v_mov_b32_e32 v2, v92
	v_mov_b32_e32 v3, v93
	v_mov_b32_e32 v4, v94
	v_mov_b32_e32 v5, v95
	s_nop 0
	s_nop 1
	v_mov_b32_e32 v28, v108
	v_mov_b32_e32 v29, v109
	v_mov_b32_e32 v30, v110
	v_mov_b32_e32 v31, v111
	s_nop 1
	v_mov_b32_e32 v32, v124
	v_mov_b32_e32 v33, v125
	v_mov_b32_e32 v34, v126
	v_mov_b32_e32 v35, v127
	v_pk_mul_f32 v[24:25], v[24:25], v[18:19] op_sel_hi:[1,0]
	v_pk_mul_f32 v[16:17], v[16:17], v[18:19] op_sel_hi:[1,0]
	v_pk_mul_f32 v[26:27], v[26:27], v[18:19] op_sel_hi:[1,0]
	v_pk_mul_f32 v[20:21], v[20:21], v[18:19] op_sel_hi:[1,0]
	v_lshlrev_b32_e32 v19, 16, v2
	v_pk_mul_f32 v[24:25], v[24:25], v[28:29]
	v_pk_mul_f32 v[16:17], v[16:17], v[32:33]
	v_and_b32_e32 v2, 0xffff0000, v2
	s_nop 0
	v_permlane16_swap_b32_e32 v24, v16
	v_permlane16_swap_b32_e32 v25, v17
	v_pk_mul_f32 v[26:27], v[26:27], v[30:31]
	v_pk_mul_f32 v[20:21], v[20:21], v[34:35]
	v_mul_f32_e32 v19, v19, v24
	v_mul_f32_e32 v2, v2, v25
	v_permlane16_swap_b32_e32 v26, v20
	v_permlane16_swap_b32_e32 v27, v21
	v_cvt_pk_bf16_f32 v2, v19, v2
	v_lshlrev_b32_e32 v19, 16, v3
	v_and_b32_e32 v3, 0xffff0000, v3
	v_mul_f32_e32 v19, v19, v26
	v_mul_f32_e32 v3, v3, v27
	v_cvt_pk_bf16_f32 v3, v19, v3
	v_lshlrev_b32_e32 v19, 16, v4
	v_and_b32_e32 v4, 0xffff0000, v4
	v_mul_f32_e32 v16, v19, v16
	v_mul_f32_e32 v4, v4, v17
	v_cvt_pk_bf16_f32 v4, v16, v4
	v_lshlrev_b32_e32 v16, 16, v5
	v_and_b32_e32 v5, 0xffff0000, v5
	v_mul_f32_e32 v5, v5, v21
	v_mul_f32_e32 v16, v16, v20
	v_cvt_pk_bf16_f32 v5, v16, v5
	global_store_dwordx4 v[14:15], v[2:5], off offset:128 sc1
	s_nop 1
	v_mov_b32_e32 v2, v96
	v_mov_b32_e32 v3, v97
	v_mov_b32_e32 v4, v98
	v_mov_b32_e32 v5, v99
	s_nop 0
	s_nop 1
	v_mov_b32_e32 v20, v112
	v_mov_b32_e32 v21, v113
	v_mov_b32_e32 v22, v114
	v_mov_b32_e32 v23, v115
	s_nop 1
	v_mov_b32_e32 v24, v128
	v_mov_b32_e32 v25, v129
	v_mov_b32_e32 v26, v130
	v_mov_b32_e32 v27, v131
	v_pk_mul_f32 v[8:9], v[8:9], v[18:19] op_sel_hi:[1,0]
	v_pk_mul_f32 v[12:13], v[12:13], v[18:19] op_sel_hi:[1,0]
	v_pk_mul_f32 v[10:11], v[10:11], v[18:19] op_sel_hi:[1,0]
	v_pk_mul_f32 v[6:7], v[6:7], v[18:19] op_sel_hi:[1,0]
	v_lshlrev_b32_e32 v0, 16, v2
	v_pk_mul_f32 v[8:9], v[8:9], v[20:21]
	v_pk_mul_f32 v[12:13], v[12:13], v[24:25]
	v_and_b32_e32 v2, 0xffff0000, v2
	s_nop 0
	v_permlane16_swap_b32_e32 v8, v12
	v_permlane16_swap_b32_e32 v9, v13
	v_pk_mul_f32 v[10:11], v[10:11], v[22:23]
	v_pk_mul_f32 v[6:7], v[6:7], v[26:27]
	v_mul_f32_e32 v0, v0, v8
	v_mul_f32_e32 v2, v2, v9
	v_permlane16_swap_b32_e32 v10, v6
	v_permlane16_swap_b32_e32 v11, v7
	v_cvt_pk_bf16_f32 v2, v0, v2
	v_lshlrev_b32_e32 v0, 16, v3
	v_and_b32_e32 v3, 0xffff0000, v3
	v_mul_f32_e32 v0, v0, v10
	v_mul_f32_e32 v3, v3, v11
	v_cvt_pk_bf16_f32 v3, v0, v3
	v_lshlrev_b32_e32 v0, 16, v4
	v_and_b32_e32 v4, 0xffff0000, v4
	v_mul_f32_e32 v0, v0, v12
	v_mul_f32_e32 v4, v4, v13
	v_cvt_pk_bf16_f32 v4, v0, v4
	v_lshlrev_b32_e32 v0, 16, v5
	v_and_b32_e32 v5, 0xffff0000, v5
	v_mul_f32_e32 v5, v5, v7
	v_mul_f32_e32 v0, v0, v6
	v_cvt_pk_bf16_f32 v5, v0, v5
	global_store_dwordx4 v[14:15], v[2:5], off offset:192 sc1
	s_cbranch_scc1 .LBB0_441

.LBB0_417:
	s_setprio 0
	v_and_b32_e32 v134, 16, v153
	v_lshrrev_b32_e32 v135, 2, v153
	v_and_or_b32 v134, v135, 8, v134
	v_mov_b64_e32 v[132:133], s[50:51]
	v_mad_u64_u32 v[132:133], s[38:39], v136, s21, v[132:133]
	v_mad_i32_i24 v133, v137, s21, v133
	v_lshl_add_u64 v[132:133], v[132:133], 0, s[30:31]
	v_lshlrev_b32_e32 v134, 1, v134
	v_mov_b32_e32 v135, 0
	v_lshl_add_u64 v[132:133], v[132:133], 0, v[134:135]
	v_lshlrev_b32_e32 v134, 4, v152
	global_load_dwordx4 v[84:87], v[132:133], off offset:1024
	global_load_dwordx4 v[100:103], v134, s[42:43]
	global_load_dwordx4 v[116:119], v134, s[42:43] offset:64
	global_load_dwordx4 v[88:91], v[132:133], off offset:1088
	global_load_dwordx4 v[104:107], v134, s[42:43] offset:128
	global_load_dwordx4 v[120:123], v134, s[42:43] offset:192
	global_load_dwordx4 v[92:95], v[132:133], off offset:1152
	global_load_dwordx4 v[108:111], v134, s[42:43] offset:256
	global_load_dwordx4 v[124:127], v134, s[42:43] offset:320
	global_load_dwordx4 v[96:99], v[132:133], off offset:1216
	global_load_dwordx4 v[112:115], v134, s[42:43] offset:384
	global_load_dwordx4 v[128:131], v134, s[42:43] offset:448
	ds_bpermute_b32 v0, v148, v162
	s_waitcnt lgkmcnt(0)
	v_add_f32_e32 v0, v162, v0
	ds_bpermute_b32 v2, v149, v0
	s_waitcnt lgkmcnt(0)
	v_add_f32_e32 v0, v0, v2
	ds_bpermute_b32 v2, v148, v160
	s_waitcnt lgkmcnt(0)
	v_add_f32_e32 v2, v160, v2
	ds_bpermute_b32 v3, v149, v2
	s_waitcnt lgkmcnt(0)
	v_add_f32_e32 v2, v2, v3
	v_div_scale_f32 v3, s[38:39], v0, v0, 1.0
	v_rcp_f32_e32 v28, v3
	s_nop 0
	v_fma_f32 v29, -v3, v28, 1.0
	v_fmac_f32_e32 v28, v29, v28
	v_div_scale_f32 v29, vcc, 1.0, v0, 1.0
	v_mul_f32_e32 v30, v29, v28
	v_fma_f32 v31, -v3, v30, v29
	v_fmac_f32_e32 v30, v31, v28
	v_fma_f32 v3, -v3, v30, v29
	v_div_fmas_f32 v3, v3, v28, v30
	v_div_fixup_f32 v0, v3, v0, 1.0
	v_div_scale_f32 v3, s[38:39], v2, v2, v150
	v_rcp_f32_e32 v28, v3
	s_nop 0
	v_fma_f32 v29, -v3, v28, 1.0
	v_fmac_f32_e32 v28, v29, v28
	v_div_scale_f32 v29, vcc, v150, v2, v150
	v_mul_f32_e32 v30, v29, v28
	v_fma_f32 v31, -v3, v30, v29
	v_fmac_f32_e32 v30, v31, v28
	v_fma_f32 v3, -v3, v30, v29
	v_div_fmas_f32 v3, v3, v28, v30
	v_div_fixup_f32 v2, v3, v2, v150
	v_pk_mul_f32 v[28:29], v[80:81], v[2:3] op_sel_hi:[1,0]
	v_pk_mul_f32 v[30:31], v[82:83], v[2:3] op_sel_hi:[1,0]
	v_pk_fma_f32 v[38:39], v[72:73], v[0:1], v[28:29] op_sel_hi:[1,0,1] neg_lo:[0,0,1] neg_hi:[0,0,1]
	v_pk_mul_f32 v[28:29], v[76:77], v[2:3] op_sel_hi:[1,0]
	v_pk_fma_f32 v[36:37], v[74:75], v[0:1], v[30:31] op_sel_hi:[1,0,1] neg_lo:[0,0,1] neg_hi:[0,0,1]
	v_pk_mul_f32 v[30:31], v[78:79], v[2:3] op_sel_hi:[1,0]
	v_pk_fma_f32 v[42:43], v[68:69], v[0:1], v[28:29] op_sel_hi:[1,0,1] neg_lo:[0,0,1] neg_hi:[0,0,1]
	v_pk_fma_f32 v[40:41], v[70:71], v[0:1], v[30:31] op_sel_hi:[1,0,1] neg_lo:[0,0,1] neg_hi:[0,0,1]
	v_mov_b32_e32 v30, v39
	v_mov_b32_e32 v31, v43
	v_mov_b32_e32 v28, v38
	v_mov_b32_e32 v29, v42
	v_pk_mul_f32 v[30:31], v[30:31], v[30:31]
	v_mov_b32_e32 v32, v37
	v_mov_b32_e32 v33, v41
	v_pk_fma_f32 v[28:29], v[28:29], v[28:29], v[30:31]
	v_mov_b32_e32 v30, v36
	v_mov_b32_e32 v31, v40
	v_pk_mul_f32 v[32:33], v[32:33], v[32:33]
	v_pk_mul_f32 v[44:45], v[44:45], v[2:3] op_sel_hi:[1,0]
	v_pk_fma_f32 v[30:31], v[30:31], v[30:31], v[32:33]
	v_pk_mul_f32 v[46:47], v[46:47], v[2:3] op_sel_hi:[1,0]
	v_pk_add_f32 v[28:29], v[28:29], v[30:31]
	v_pk_mul_f32 v[30:31], v[66:67], v[2:3] op_sel_hi:[1,0]
	v_pk_add_f32 v[68:69], v[28:29], v[28:29] op_sel_hi:[0,1]
	v_pk_mul_f32 v[28:29], v[64:65], v[2:3] op_sel_hi:[1,0]
	v_pk_fma_f32 v[30:31], v[62:63], v[0:1], v[30:31] op_sel_hi:[1,0,1] neg_lo:[0,0,1] neg_hi:[0,0,1]
	v_pk_fma_f32 v[28:29], v[60:61], v[0:1], v[28:29] op_sel_hi:[1,0,1] neg_lo:[0,0,1] neg_hi:[0,0,1]
	v_pk_mul_f32 v[32:33], v[30:31], v[30:31]
	v_pk_mul_f32 v[34:35], v[28:29], v[28:29]
	v_pk_fma_f32 v[26:27], v[26:27], v[0:1], v[46:47] op_sel_hi:[1,0,1] neg_lo:[0,0,1] neg_hi:[0,0,1]
	v_pk_mov_b32 v[60:61], v[34:35], v[32:33] op_sel:[1,0]
	v_mov_b32_e32 v35, v33
	v_pk_add_f32 v[32:33], v[60:61], v[34:35]
	v_pk_mul_f32 v[34:35], v[56:57], v[2:3] op_sel_hi:[1,0]
	v_pk_add_f32 v[60:61], v[32:33], v[32:33] op_sel_hi:[0,1]
	v_pk_fma_f32 v[34:35], v[48:49], v[0:1], v[34:35] op_sel_hi:[1,0,1] neg_lo:[0,0,1] neg_hi:[0,0,1]
	v_pk_mul_f32 v[32:33], v[58:59], v[2:3] op_sel_hi:[1,0]
	v_mul_f32_e32 v48, v34, v34
	v_pk_fma_f32 v[32:33], v[50:51], v[0:1], v[32:33] op_sel_hi:[1,0,1] neg_lo:[0,0,1] neg_hi:[0,0,1]
	v_pk_fma_f32 v[48:49], v[34:35], v[34:35], v[48:49] op_sel_hi:[1,1,0]
	v_pk_fma_f32 v[24:25], v[24:25], v[0:1], v[44:45] op_sel_hi:[1,0,1] neg_lo:[0,0,1] neg_hi:[0,0,1]
	v_mul_f32_e32 v48, v32, v32
	v_pk_fma_f32 v[50:51], v[32:33], v[32:33], v[48:49] op_sel_hi:[1,1,0]
	v_pk_mul_f32 v[22:23], v[22:23], v[2:3] op_sel_hi:[1,0]
	v_pk_mul_f32 v[20:21], v[20:21], v[2:3] op_sel_hi:[1,0]
	v_pk_mul_f32 v[12:13], v[12:13], v[2:3] op_sel_hi:[1,0]
	v_mul_f32_e32 v48, v24, v24
	v_mul_f32_e32 v50, v25, v25
	v_mul_f32_e32 v60, v26, v26
	v_mul_f32_e32 v68, v27, v27
	v_pk_fma_f32 v[16:17], v[16:17], v[0:1], v[20:21] op_sel_hi:[1,0,1] neg_lo:[0,0,1] neg_hi:[0,0,1]
	v_pk_fma_f32 v[20:21], v[18:19], v[0:1], v[22:23] op_sel_hi:[1,0,1] neg_lo:[0,0,1] neg_hi:[0,0,1]
	v_pk_mul_f32 v[14:15], v[14:15], v[2:3] op_sel_hi:[1,0]
	v_pk_fma_f32 v[8:9], v[8:9], v[0:1], v[12:13] op_sel_hi:[1,0,1] neg_lo:[0,0,1] neg_hi:[0,0,1]
	v_pk_add_f32 v[44:45], v[48:49], v[50:51]
	v_pk_add_f32 v[46:47], v[60:61], v[68:69]
	v_pk_mul_f32 v[18:19], v[20:21], v[20:21]
	v_pk_mul_f32 v[22:23], v[16:17], v[16:17]
	v_pk_fma_f32 v[10:11], v[10:11], v[0:1], v[14:15] op_sel_hi:[1,0,1] neg_lo:[0,0,1] neg_hi:[0,0,1]
	v_mul_f32_e32 v12, v8, v8
	v_pk_add_f32 v[44:45], v[44:45], v[46:47]
	v_pk_mov_b32 v[46:47], v[22:23], v[18:19] op_sel:[1,0]
	v_mov_b32_e32 v23, v19
	v_pk_fma_f32 v[14:15], v[8:9], v[8:9], v[12:13] op_sel_hi:[1,1,0]
	v_mul_f32_e32 v12, v10, v10
	v_pk_add_f32 v[18:19], v[46:47], v[22:23]
	v_pk_fma_f32 v[22:23], v[10:11], v[10:11], v[12:13] op_sel_hi:[1,1,0]
	v_pk_mul_f32 v[12:13], v[52:53], v[2:3] op_sel_hi:[1,0]
	v_pk_mul_f32 v[2:3], v[54:55], v[2:3] op_sel_hi:[1,0]
	v_pk_add_f32 v[44:45], v[44:45], v[44:45] op_sel_hi:[0,1]
	v_pk_add_f32 v[18:19], v[18:19], v[18:19] op_sel_hi:[0,1]
	v_pk_fma_f32 v[6:7], v[6:7], v[0:1], v[2:3] op_sel_hi:[1,0,1] neg_lo:[0,0,1] neg_hi:[0,0,1]
	v_pk_fma_f32 v[12:13], v[4:5], v[0:1], v[12:13] op_sel_hi:[1,0,1] neg_lo:[0,0,1] neg_hi:[0,0,1]
	v_mul_f32_e32 v18, v6, v6
	v_mul_f32_e32 v14, v12, v12
	v_mul_f32_e32 v22, v13, v13
	v_mul_f32_e32 v44, v7, v7
	v_pk_add_f32 v[2:3], v[14:15], v[22:23]
	v_pk_add_f32 v[4:5], v[18:19], v[44:45]
	s_nop 0
	v_pk_add_f32 v[2:3], v[2:3], v[4:5]
	s_nop 0
	v_add_f32_e32 v0, v2, v3
	ds_bpermute_b32 v2, v148, v0
	s_waitcnt lgkmcnt(0)
	v_add_f32_e32 v0, v0, v2
	ds_bpermute_b32 v2, v149, v0
	s_waitcnt lgkmcnt(0)
	v_add_f32_e32 v0, v0, v2
	v_fmamk_f32 v0, v0, 0x3c000000, v227
	v_cmp_gt_f32_e32 vcc, s7, v0
	v_mul_f32_e32 v2, 0x4f800000, v0
	s_nop 0
	v_cndmask_b32_e32 v0, v0, v2, vcc
	v_sqrt_f32_e32 v2, v0
	s_nop 0
	v_add_u32_e32 v3, -1, v2
	v_fma_f32 v4, -v3, v2, v0
	v_cmp_ge_f32_e64 s[38:39], 0, v4
	v_add_u32_e32 v4, 1, v2
	s_nop 0
	v_cndmask_b32_e64 v3, v2, v3, s[38:39]
	v_fma_f32 v2, -v4, v2, v0
	v_cmp_lt_f32_e64 s[38:39], 0, v2
	s_nop 1
	v_cndmask_b32_e64 v2, v3, v4, s[38:39]
	v_mul_f32_e32 v3, 0x37800000, v2
	v_cndmask_b32_e32 v2, v2, v3, vcc
	v_cmp_class_f32_e32 vcc, v0, v228
	s_nop 1
	v_cndmask_b32_e32 v0, v2, v0, vcc
	v_div_scale_f32 v2, s[38:39], v0, v0, v151
	v_rcp_f32_e32 v3, v2
	s_nop 0
	v_fma_f32 v4, -v2, v3, 1.0
	v_fmac_f32_e32 v3, v4, v3
	v_div_scale_f32 v4, vcc, v151, v0, v151
	v_mul_f32_e32 v5, v4, v3
	v_fma_f32 v14, -v2, v5, v4
	v_fmac_f32_e32 v5, v14, v3
	v_fma_f32 v2, -v2, v5, v4
	v_div_fmas_f32 v2, v2, v3, v5
	v_div_fixup_f32 v18, v2, v0, v151
	v_and_b32_e32 v0, 16, v153
	v_lshrrev_b32_e32 v2, 2, v153
	v_and_or_b32 v0, v2, 8, v0
	v_mov_b64_e32 v[2:3], s[50:51]
	v_mad_u64_u32 v[2:3], s[38:39], v136, s21, v[2:3]
	v_mad_i32_i24 v3, v137, s21, v3
	v_lshl_add_u64 v[2:3], v[2:3], 0, s[30:31]
	v_lshlrev_b32_e32 v0, 1, v0
	v_lshl_add_u64 v[22:23], v[2:3], 0, v[0:1]
	v_lshl_add_u64 v[14:15], v[138:139], 0, v[0:1]
	v_lshlrev_b32_e32 v0, 4, v152
	s_waitcnt vmcnt(0)
	v_mov_b32_e32 v2, v84
	v_mov_b32_e32 v3, v85
	v_mov_b32_e32 v4, v86
	v_mov_b32_e32 v5, v87
	s_nop 1
	v_mov_b32_e32 v44, v100
	v_mov_b32_e32 v45, v101
	v_mov_b32_e32 v46, v102
	v_mov_b32_e32 v47, v103
	s_nop 1
	v_mov_b32_e32 v48, v116
	v_mov_b32_e32 v49, v117
	v_mov_b32_e32 v50, v118
	v_mov_b32_e32 v51, v119
	v_pk_mul_f32 v[38:39], v[38:39], v[18:19] op_sel_hi:[1,0]
	v_pk_mul_f32 v[42:43], v[42:43], v[18:19] op_sel_hi:[1,0]
	v_pk_mul_f32 v[36:37], v[36:37], v[18:19] op_sel_hi:[1,0]
	v_pk_mul_f32 v[40:41], v[40:41], v[18:19] op_sel_hi:[1,0]
	v_mov_b32_e32 v153, v224
	s_lshl_b32 s39, s16, 7
	v_lshlrev_b32_e32 v19, 16, v2
	v_pk_mul_f32 v[38:39], v[44:45], v[38:39]
	v_pk_mul_f32 v[42:43], v[48:49], v[42:43]
	v_and_b32_e32 v2, 0xffff0000, v2
	s_nop 0
	v_permlane16_swap_b32_e32 v38, v42
	v_permlane16_swap_b32_e32 v39, v43
	v_pk_mul_f32 v[36:37], v[46:47], v[36:37]
	v_pk_mul_f32 v[40:41], v[50:51], v[40:41]
	v_mul_f32_e32 v19, v19, v38
	v_mul_f32_e32 v2, v2, v39
	v_permlane16_swap_b32_e32 v36, v40
	v_permlane16_swap_b32_e32 v37, v41
	v_cvt_pk_bf16_f32 v2, v19, v2
	v_lshlrev_b32_e32 v19, 16, v3
	v_and_b32_e32 v3, 0xffff0000, v3
	v_mul_f32_e32 v19, v19, v36
	v_mul_f32_e32 v3, v3, v37
	v_cvt_pk_bf16_f32 v3, v19, v3
	v_lshlrev_b32_e32 v19, 16, v4
	v_and_b32_e32 v4, 0xffff0000, v4
	v_mul_f32_e32 v19, v19, v42
	v_mul_f32_e32 v4, v4, v43
	v_cvt_pk_bf16_f32 v4, v19, v4
	v_lshlrev_b32_e32 v19, 16, v5
	v_and_b32_e32 v5, 0xffff0000, v5
	v_mul_f32_e32 v5, v5, v41
	v_mul_f32_e32 v19, v19, v40
	v_cvt_pk_bf16_f32 v5, v19, v5
	global_store_dwordx4 v[14:15], v[2:5], off sc1
	s_nop 1
	v_mov_b32_e32 v2, v88
	v_mov_b32_e32 v3, v89
	v_mov_b32_e32 v4, v90
	v_mov_b32_e32 v5, v91
	s_nop 0
	s_nop 1
	v_mov_b32_e32 v36, v104
	v_mov_b32_e32 v37, v105
	v_mov_b32_e32 v38, v106
	v_mov_b32_e32 v39, v107
	s_nop 1
	v_mov_b32_e32 v40, v120
	v_mov_b32_e32 v41, v121
	v_mov_b32_e32 v42, v122
	v_mov_b32_e32 v43, v123
	v_pk_mul_f32 v[28:29], v[28:29], v[18:19] op_sel_hi:[1,0]
	v_pk_mul_f32 v[34:35], v[34:35], v[18:19] op_sel_hi:[1,0]
	v_pk_mul_f32 v[30:31], v[30:31], v[18:19] op_sel_hi:[1,0]
	v_pk_mul_f32 v[32:33], v[32:33], v[18:19] op_sel_hi:[1,0]
	v_lshlrev_b32_e32 v19, 16, v2
	v_pk_mul_f32 v[28:29], v[36:37], v[28:29]
	v_pk_mul_f32 v[34:35], v[40:41], v[34:35]
	v_and_b32_e32 v2, 0xffff0000, v2
	s_nop 0
	v_permlane16_swap_b32_e32 v28, v34
	v_permlane16_swap_b32_e32 v29, v35
	v_pk_mul_f32 v[30:31], v[38:39], v[30:31]
	v_pk_mul_f32 v[32:33], v[42:43], v[32:33]
	v_mul_f32_e32 v19, v19, v28
	v_mul_f32_e32 v2, v2, v29
	v_permlane16_swap_b32_e32 v30, v32
	v_permlane16_swap_b32_e32 v31, v33
	v_cvt_pk_bf16_f32 v2, v19, v2
	v_lshlrev_b32_e32 v19, 16, v3
	v_and_b32_e32 v3, 0xffff0000, v3
	v_mul_f32_e32 v19, v19, v30
	v_mul_f32_e32 v3, v3, v31
	v_cvt_pk_bf16_f32 v3, v19, v3
	v_lshlrev_b32_e32 v19, 16, v4
	v_and_b32_e32 v4, 0xffff0000, v4
	v_mul_f32_e32 v19, v19, v34
	v_mul_f32_e32 v4, v4, v35
	v_cvt_pk_bf16_f32 v4, v19, v4
	v_lshlrev_b32_e32 v19, 16, v5
	v_and_b32_e32 v5, 0xffff0000, v5
	v_mul_f32_e32 v5, v5, v33
	v_mul_f32_e32 v19, v19, v32
	v_cvt_pk_bf16_f32 v5, v19, v5
	global_store_dwordx4 v[14:15], v[2:5], off offset:64 sc1
	s_nop 1
	v_mov_b32_e32 v2, v92
	v_mov_b32_e32 v3, v93
	v_mov_b32_e32 v4, v94
	v_mov_b32_e32 v5, v95
	s_nop 0
	s_nop 1
	v_mov_b32_e32 v28, v108
	v_mov_b32_e32 v29, v109
	v_mov_b32_e32 v30, v110
	v_mov_b32_e32 v31, v111
	s_nop 1
	v_mov_b32_e32 v32, v124
	v_mov_b32_e32 v33, v125
	v_mov_b32_e32 v34, v126
	v_mov_b32_e32 v35, v127
	v_pk_mul_f32 v[24:25], v[24:25], v[18:19] op_sel_hi:[1,0]
	v_pk_mul_f32 v[16:17], v[16:17], v[18:19] op_sel_hi:[1,0]
	v_pk_mul_f32 v[26:27], v[26:27], v[18:19] op_sel_hi:[1,0]
	v_pk_mul_f32 v[20:21], v[20:21], v[18:19] op_sel_hi:[1,0]
	v_lshlrev_b32_e32 v19, 16, v2
	v_pk_mul_f32 v[24:25], v[24:25], v[28:29]
	v_pk_mul_f32 v[16:17], v[16:17], v[32:33]
	v_and_b32_e32 v2, 0xffff0000, v2
	s_nop 0
	v_permlane16_swap_b32_e32 v24, v16
	v_permlane16_swap_b32_e32 v25, v17
	v_pk_mul_f32 v[26:27], v[26:27], v[30:31]
	v_pk_mul_f32 v[20:21], v[20:21], v[34:35]
	v_mul_f32_e32 v19, v19, v24
	v_mul_f32_e32 v2, v2, v25
	v_permlane16_swap_b32_e32 v26, v20
	v_permlane16_swap_b32_e32 v27, v21
	v_cvt_pk_bf16_f32 v2, v19, v2
	v_lshlrev_b32_e32 v19, 16, v3
	v_and_b32_e32 v3, 0xffff0000, v3
	v_mul_f32_e32 v19, v19, v26
	v_mul_f32_e32 v3, v3, v27
	v_cvt_pk_bf16_f32 v3, v19, v3
	v_lshlrev_b32_e32 v19, 16, v4
	v_and_b32_e32 v4, 0xffff0000, v4
	v_mul_f32_e32 v16, v19, v16
	v_mul_f32_e32 v4, v4, v17
	v_cvt_pk_bf16_f32 v4, v16, v4
	v_lshlrev_b32_e32 v16, 16, v5
	v_and_b32_e32 v5, 0xffff0000, v5
	v_mul_f32_e32 v5, v5, v21
	v_mul_f32_e32 v16, v16, v20
	v_cvt_pk_bf16_f32 v5, v16, v5
	global_store_dwordx4 v[14:15], v[2:5], off offset:128 sc1
	s_nop 1
	v_mov_b32_e32 v2, v96
	v_mov_b32_e32 v3, v97
	v_mov_b32_e32 v4, v98
	v_mov_b32_e32 v5, v99
	s_nop 0
	s_nop 1
	v_mov_b32_e32 v20, v112
	v_mov_b32_e32 v21, v113
	v_mov_b32_e32 v22, v114
	v_mov_b32_e32 v23, v115
	s_nop 1
	v_mov_b32_e32 v24, v128
	v_mov_b32_e32 v25, v129
	v_mov_b32_e32 v26, v130
	v_mov_b32_e32 v27, v131
	v_pk_mul_f32 v[8:9], v[8:9], v[18:19] op_sel_hi:[1,0]
	v_pk_mul_f32 v[12:13], v[12:13], v[18:19] op_sel_hi:[1,0]
	v_pk_mul_f32 v[10:11], v[10:11], v[18:19] op_sel_hi:[1,0]
	v_pk_mul_f32 v[6:7], v[6:7], v[18:19] op_sel_hi:[1,0]
	v_lshlrev_b32_e32 v0, 16, v2
	v_pk_mul_f32 v[8:9], v[8:9], v[20:21]
	v_pk_mul_f32 v[12:13], v[12:13], v[24:25]
	v_and_b32_e32 v2, 0xffff0000, v2
	s_nop 0
	v_permlane16_swap_b32_e32 v8, v12
	v_permlane16_swap_b32_e32 v9, v13
	v_pk_mul_f32 v[10:11], v[10:11], v[22:23]
	v_pk_mul_f32 v[6:7], v[6:7], v[26:27]
	v_mul_f32_e32 v0, v0, v8
	v_mul_f32_e32 v2, v2, v9
	v_permlane16_swap_b32_e32 v10, v6
	v_permlane16_swap_b32_e32 v11, v7
	v_cvt_pk_bf16_f32 v2, v0, v2
	v_lshlrev_b32_e32 v0, 16, v3
	v_and_b32_e32 v3, 0xffff0000, v3
	v_mul_f32_e32 v0, v0, v10
	v_mul_f32_e32 v3, v3, v11
	v_cvt_pk_bf16_f32 v3, v0, v3
	v_lshlrev_b32_e32 v0, 16, v4
	v_and_b32_e32 v4, 0xffff0000, v4
	v_mul_f32_e32 v0, v0, v12
	v_mul_f32_e32 v4, v4, v13
	v_cvt_pk_bf16_f32 v4, v0, v4
	v_lshlrev_b32_e32 v0, 16, v5
	v_and_b32_e32 v5, 0xffff0000, v5
	v_mul_f32_e32 v5, v5, v7
	v_mul_f32_e32 v0, v0, v6
	v_cvt_pk_bf16_f32 v5, v0, v5
	global_store_dwordx4 v[14:15], v[2:5], off offset:192 sc1
	s_nop 0
	v_readfirstlane_b32 s38, v153
	s_ashr_i32 s38, s38, 6
	s_lshl_b32 s62, s38, 4
	v_and_b32_e32 v2, 15, v153
	s_add_i32 s62, s62, s39
	v_or_b32_e32 v4, s62, v2
	v_ashrrev_i32_e32 v5, 31, v4
	v_lshl_add_u64 v[136:137], s[44:45], 0, v[4:5]
	v_mov_b64_e32 v[4:5], s[28:29]
	v_mad_u64_u32 v[4:5], s[62:63], v136, s23, v[4:5]
	v_mad_i32_i24 v5, v137, s23, v5
	v_lshl_add_u64 v[138:139], v[4:5], 0, s[30:31]
	v_and_b32_e32 v0, 48, v153
	v_lshl_add_u64 v[4:5], v[138:139], 0, v[0:1]
	global_load_dwordx4 v[36:39], v[4:5], off
	global_load_dwordx4 v[40:43], v[4:5], off offset:64
	global_load_dwordx4 v[44:47], v[4:5], off offset:128
	global_load_dwordx4 v[52:55], v[4:5], off offset:192
	s_cmp_lt_i32 s38, 4
	s_cbranch_scc1 .LBB0_419
	s_setprio 0
